# P0 rmsnorm loop: norm-gain quads loaded once before the row loop (were reloaded per row pair with vmcnt(0) waits)
# speedup vs baseline: 1.0009x; 1.0009x over previous
.LBB0_216:
	s_lshl_b32 s0, s2, 3
	s_add_i32 s0, s3, s0
	s_lshl_b32 s33, s30, 3
	s_add_u32 s22, s28, 0x1a80000
	s_addc_u32 s23, s29, 0
	s_waitcnt lgkmcnt(0)
	s_add_u32 s56, s28, 0x9a80000
	s_addc_u32 s57, s29, 0
	s_cmpk_gt_i32 s0, 0x3fff
	v_mbcnt_lo_u32_b32 v248, -1, 0
	s_cbranch_scc1 .LBB0_219
	s_waitcnt vmcnt(11)
	v_mbcnt_hi_u32_b32 v2, -1, v248
	v_and_b32_e32 v3, 64, v2
	v_add_u32_e32 v3, 64, v3
	s_waitcnt vmcnt(10)
	v_xor_b32_e32 v4, 1, v2
	v_cmp_lt_i32_e32 vcc, v4, v3
	v_lshlrev_b32_e32 v0, 4, v44
	v_mov_b32_e32 v1, 0
	v_cndmask_b32_e32 v4, v2, v4, vcc
	s_waitcnt vmcnt(5)
	v_lshlrev_b32_e32 v24, 2, v4
	v_xor_b32_e32 v4, 2, v2
	v_cmp_lt_i32_e32 vcc, v4, v3
	v_lshl_add_u64 v[8:9], s[52:53], 0, v[0:1]
	v_lshl_add_u64 v[10:11], s[54:55], 0, v[0:1]
	v_cndmask_b32_e32 v4, v2, v4, vcc
	v_lshlrev_b32_e32 v25, 2, v4
	v_xor_b32_e32 v4, 4, v2
	v_cmp_lt_i32_e32 vcc, v4, v3
	v_lshlrev_b32_e32 v0, 3, v44
	v_lshl_add_u64 v[12:13], s[22:23], 0, v[0:1]
	v_cndmask_b32_e32 v4, v2, v4, vcc
	v_lshlrev_b32_e32 v26, 2, v4
	v_xor_b32_e32 v4, 8, v2
	v_cmp_lt_i32_e32 vcc, v4, v3
	v_lshl_add_u64 v[14:15], s[56:57], 0, v[0:1]
	s_waitcnt vmcnt(4)
	v_mov_b32_e32 v30, 0x358637bd
	v_cndmask_b32_e32 v4, v2, v4, vcc
	v_lshlrev_b32_e32 v27, 2, v4
	v_xor_b32_e32 v4, 16, v2
	v_cmp_lt_i32_e32 vcc, v4, v3
	s_nop 1
	v_cndmask_b32_e32 v4, v2, v4, vcc
	v_lshlrev_b32_e32 v28, 2, v4
	v_xor_b32_e32 v4, 32, v2
	v_cmp_lt_i32_e32 vcc, v4, v3
	s_nop 1
	v_cndmask_b32_e32 v2, v2, v4, vcc
	v_lshlrev_b32_e32 v29, 2, v2
	global_load_dwordx4 v[200:203], v[10:11], off
	global_load_dwordx4 v[204:207], v[10:11], off offset:1024
	global_load_dwordx4 v[208:211], v[10:11], off offset:2048
	global_load_dwordx4 v[212:215], v[10:11], off offset:3072
.LBB0_218:
	s_add_i32 s3, s0, s33
	s_cmpk_lt_i32 s3, 0x4000
	s_cselect_b32 s4, s3, s0
	s_ashr_i32 s1, s0, 31
	s_lshl_b64 s[6:7], s[0:1], 12
	s_ashr_i32 s5, s4, 31
	v_lshl_add_u64 v[20:21], v[8:9], 0, s[6:7]
	s_lshl_b64 s[6:7], s[4:5], 12
	global_load_dwordx4 v[32:35], v[20:21], off nt
	global_load_dwordx4 v[36:39], v[20:21], off offset:1024 nt
	global_load_dwordx4 v[0:3], v[20:21], off offset:3072 nt
	global_load_dwordx4 v[40:43], v[20:21], off offset:2048 nt
	v_lshl_add_u64 v[60:61], v[8:9], 0, s[6:7]
	global_load_dwordx4 v[44:47], v[60:61], off nt
	global_load_dwordx4 v[48:51], v[60:61], off offset:1024 nt
	global_load_dwordx4 v[52:55], v[60:61], off offset:3072 nt
	global_load_dwordx4 v[56:59], v[60:61], off offset:2048 nt
	s_lshl_b64 s[18:19], s[0:1], 11
	v_lshl_add_u64 v[16:17], v[12:13], 0, s[18:19]
	s_lshl_b64 s[0:1], s[4:5], 11
	v_lshl_add_u64 v[20:21], v[12:13], 0, s[0:1]
	v_lshl_add_u64 v[18:19], v[14:15], 0, s[18:19]
	v_lshl_add_u64 v[22:23], v[14:15], 0, s[0:1]
	s_add_i32 s0, s3, s33
	s_cmpk_lt_i32 s0, 0x4000
	s_waitcnt vmcnt(7)
	v_pk_mul_f32 v[60:61], v[34:35], v[34:35]
	v_pk_mul_f32 v[62:63], v[32:33], v[32:33]
	s_waitcnt vmcnt(6)
	v_pk_mul_f32 v[64:65], v[38:39], v[38:39]
	v_pk_mul_f32 v[66:67], v[36:37], v[36:37]
	s_waitcnt vmcnt(4)
	v_mul_f32_e32 v68, v41, v41
	v_mul_f32_e32 v70, v43, v43
	v_pk_mov_b32 v[72:73], v[62:63], v[60:61] op_sel:[1,0]
	v_mov_b32_e32 v63, v61
	s_waitcnt vmcnt(3)
	v_pk_mul_f32 v[60:61], v[46:47], v[46:47]
	v_pk_mul_f32 v[74:75], v[44:45], v[44:45]
	v_pk_mov_b32 v[76:77], v[66:67], v[64:65] op_sel:[1,0]
	v_mov_b32_e32 v67, v65
	s_waitcnt vmcnt(2)
	v_pk_mul_f32 v[64:65], v[50:51], v[50:51]
	v_pk_mul_f32 v[78:79], v[48:49], v[48:49]
	v_mul_f32_e32 v31, v2, v2
	v_mul_f32_e32 v81, v3, v3
	v_pk_fma_f32 v[68:69], v[40:41], v[40:41], v[68:69] op_sel_hi:[1,1,0]
	v_pk_fma_f32 v[70:71], v[42:43], v[42:43], v[70:71] op_sel_hi:[1,1,0]
	v_pk_add_f32 v[62:63], v[72:73], v[62:63]
	v_pk_mov_b32 v[72:73], v[74:75], v[60:61] op_sel:[1,0]
	v_mov_b32_e32 v75, v61
	v_pk_add_f32 v[60:61], v[76:77], v[66:67]
	v_pk_mov_b32 v[66:67], v[78:79], v[64:65] op_sel:[1,0]
	v_mov_b32_e32 v79, v65
	v_mul_f32_e32 v83, v0, v0
	v_mul_f32_e32 v84, v1, v1
	s_waitcnt vmcnt(0)
	v_mul_f32_e32 v80, v57, v57
	v_mul_f32_e32 v82, v59, v59
	v_mov_b32_e32 v69, v31
	v_mov_b32_e32 v71, v81
	v_pk_add_f32 v[72:73], v[72:73], v[74:75]
	v_pk_add_f32 v[66:67], v[66:67], v[78:79]
	v_pk_add_f32 v[62:63], v[62:63], v[62:63] op_sel:[0,1] op_sel_hi:[1,0]
	v_pk_add_f32 v[60:61], v[60:61], v[60:61] op_sel:[0,1] op_sel_hi:[1,0]
	v_mul_f32_e32 v85, v54, v54
	v_mul_f32_e32 v86, v55, v55
	v_mul_f32_e32 v87, v52, v52
	v_mul_f32_e32 v88, v53, v53
	v_pk_fma_f32 v[64:65], v[56:57], v[56:57], v[80:81] op_sel_hi:[1,1,0]
	v_pk_fma_f32 v[76:77], v[58:59], v[58:59], v[82:83] op_sel_hi:[1,1,0]
	v_pk_add_f32 v[68:69], v[68:69], v[70:71]
	v_mov_b32_e32 v63, v83
	v_mov_b32_e32 v61, v84
	v_pk_add_f32 v[70:71], v[72:73], v[72:73] op_sel:[0,1] op_sel_hi:[1,0]
	v_pk_add_f32 v[66:67], v[66:67], v[66:67] op_sel:[0,1] op_sel_hi:[1,0]
	v_mov_b32_e32 v65, v85
	v_mov_b32_e32 v77, v86
	v_pk_add_f32 v[60:61], v[62:63], v[60:61]
	v_mov_b32_e32 v71, v87
	v_mov_b32_e32 v67, v88
	v_pk_add_f32 v[64:65], v[64:65], v[76:77]
	v_pk_add_f32 v[60:61], v[60:61], v[68:69]
	v_pk_add_f32 v[62:63], v[70:71], v[66:67]
	v_add_f32_e32 v31, v60, v61
	v_pk_add_f32 v[60:61], v[62:63], v[64:65]
	s_nop 1
	v_mov_b32_dpp v62, v31 quad_perm:[1,0,3,2] row_mask:0xf bank_mask:0xf
	v_add_f32_e32 v60, v60, v61
	s_nop 1
	v_mov_b32_dpp v61, v60 quad_perm:[1,0,3,2] row_mask:0xf bank_mask:0xf
	s_waitcnt lgkmcnt(1)
	v_add_f32_e32 v31, v31, v62
	s_nop 1
	v_mov_b32_dpp v62, v31 quad_perm:[2,3,0,1] row_mask:0xf bank_mask:0xf
	s_waitcnt lgkmcnt(1)
	v_add_f32_e32 v60, v60, v61
	s_nop 1
	v_mov_b32_dpp v61, v60 quad_perm:[2,3,0,1] row_mask:0xf bank_mask:0xf
	s_waitcnt lgkmcnt(1)
	v_add_f32_e32 v31, v31, v62
	s_nop 1
	v_mov_b32_dpp v62, v31 row_half_mirror row_mask:0xf bank_mask:0xf
	s_waitcnt lgkmcnt(1)
	v_add_f32_e32 v60, v60, v61
	s_nop 1
	v_mov_b32_dpp v61, v60 row_half_mirror row_mask:0xf bank_mask:0xf
	s_waitcnt lgkmcnt(1)
	v_add_f32_e32 v31, v31, v62
	s_nop 1
	v_mov_b32_dpp v62, v31 row_mirror row_mask:0xf bank_mask:0xf
	s_waitcnt lgkmcnt(1)
	v_add_f32_e32 v60, v60, v61
	s_nop 1
	v_mov_b32_dpp v61, v60 row_mirror row_mask:0xf bank_mask:0xf
	s_waitcnt lgkmcnt(1)
	v_add_f32_e32 v31, v31, v62
	v_mov_b32_e32 v62, v31
	s_nop 1
	v_permlane16_swap_b32_e32 v31, v62
	s_nop 1
	s_waitcnt lgkmcnt(1)
	v_add_f32_e32 v60, v60, v61
	v_mov_b32_e32 v61, v60
	s_nop 1
	v_permlane16_swap_b32_e32 v60, v61
	s_nop 1
	s_waitcnt lgkmcnt(1)
	v_add_f32_e32 v31, v31, v62
	v_mov_b32_e32 v62, v31
	s_nop 1
	v_permlane32_swap_b32_e32 v31, v62
	s_nop 1
	s_waitcnt lgkmcnt(1)
	v_add_f32_e32 v60, v60, v61
	v_mov_b32_e32 v61, v60
	s_nop 1
	v_permlane32_swap_b32_e32 v60, v61
	s_nop 1
	s_waitcnt lgkmcnt(1)
	v_add_f32_e32 v31, v31, v62
	v_fmamk_f32 v31, v31, 0x3a800000, v30
	s_waitcnt lgkmcnt(0)
	v_add_f32_e32 v61, v60, v61
	v_rsq_f32_e32 v60, v31
	v_fmamk_f32 v31, v61, 0x3a800000, v30
	v_rsq_f32_e32 v62, v31
	v_pk_mul_f32 v[64:65], v[32:33], v[60:61] op_sel_hi:[1,0]
	v_pk_mul_f32 v[66:67], v[34:35], v[60:61] op_sel_hi:[1,0]
	v_pk_mul_f32 v[68:69], v[44:45], v[62:63] op_sel_hi:[1,0]
	v_pk_mul_f32 v[64:65], v[200:201], v[64:65]
	v_pk_mul_f32 v[70:71], v[46:47], v[62:63] op_sel_hi:[1,0]
	v_pk_mul_f32 v[4:5], v[200:201], v[68:69]
	v_pk_mul_f32 v[66:67], v[202:203], v[66:67]
	v_pk_mul_f32 v[6:7], v[202:203], v[70:71]
	v_cvt_pk_bf16_f32 v64, v64, v65
	v_cvt_pk_bf16_f32 v65, v66, v67
	global_store_dwordx2 v[16:17], v[64:65], off
	v_cvt_pk_bf16_f32 v4, v4, v5
	v_cvt_pk_bf16_f32 v5, v6, v7
	global_store_dwordx2 v[20:21], v[4:5], off
	v_cvt_pk_bf16_f32 v4, v32, v33
	v_cvt_pk_bf16_f32 v5, v34, v35
	global_store_dwordx2 v[18:19], v[4:5], off
	v_cvt_pk_bf16_f32 v4, v44, v45
	v_cvt_pk_bf16_f32 v5, v46, v47
	global_store_dwordx2 v[22:23], v[4:5], off
	v_pk_mul_f32 v[32:33], v[36:37], v[60:61] op_sel_hi:[1,0]
	v_pk_mul_f32 v[44:45], v[48:49], v[62:63] op_sel_hi:[1,0]
	v_pk_mul_f32 v[34:35], v[38:39], v[60:61] op_sel_hi:[1,0]
	v_pk_mul_f32 v[46:47], v[50:51], v[62:63] op_sel_hi:[1,0]
	v_pk_mul_f32 v[32:33], v[32:33], v[204:205]
	v_pk_mul_f32 v[4:5], v[44:45], v[204:205]
	v_pk_mul_f32 v[34:35], v[34:35], v[206:207]
	v_pk_mul_f32 v[6:7], v[46:47], v[206:207]
	v_cvt_pk_bf16_f32 v32, v32, v33
	v_cvt_pk_bf16_f32 v33, v34, v35
	global_store_dwordx2 v[16:17], v[32:33], off offset:512
	v_cvt_pk_bf16_f32 v4, v4, v5
	v_cvt_pk_bf16_f32 v5, v6, v7
	global_store_dwordx2 v[20:21], v[4:5], off offset:512
	v_cvt_pk_bf16_f32 v4, v36, v37
	v_cvt_pk_bf16_f32 v5, v38, v39
	global_store_dwordx2 v[18:19], v[4:5], off offset:512
	v_cvt_pk_bf16_f32 v4, v48, v49
	v_cvt_pk_bf16_f32 v5, v50, v51
	global_store_dwordx2 v[22:23], v[4:5], off offset:512
	v_pk_mul_f32 v[32:33], v[40:41], v[60:61] op_sel_hi:[1,0]
	v_pk_mul_f32 v[36:37], v[56:57], v[62:63] op_sel_hi:[1,0]
	v_pk_mul_f32 v[34:35], v[42:43], v[60:61] op_sel_hi:[1,0]
	v_pk_mul_f32 v[38:39], v[58:59], v[62:63] op_sel_hi:[1,0]
	v_pk_mul_f32 v[32:33], v[32:33], v[208:209]
	v_pk_mul_f32 v[4:5], v[36:37], v[208:209]
	v_pk_mul_f32 v[34:35], v[34:35], v[210:211]
	v_pk_mul_f32 v[6:7], v[38:39], v[210:211]
	v_cvt_pk_bf16_f32 v32, v32, v33
	v_cvt_pk_bf16_f32 v33, v34, v35
	global_store_dwordx2 v[16:17], v[32:33], off offset:1024
	v_cvt_pk_bf16_f32 v4, v4, v5
	v_cvt_pk_bf16_f32 v5, v6, v7
	global_store_dwordx2 v[20:21], v[4:5], off offset:1024
	v_cvt_pk_bf16_f32 v4, v40, v41
	v_cvt_pk_bf16_f32 v5, v42, v43
	global_store_dwordx2 v[18:19], v[4:5], off offset:1024
	v_cvt_pk_bf16_f32 v4, v56, v57
	v_cvt_pk_bf16_f32 v5, v58, v59
	global_store_dwordx2 v[22:23], v[4:5], off offset:1024
	v_pk_mul_f32 v[32:33], v[0:1], v[60:61] op_sel_hi:[1,0]
	v_pk_mul_f32 v[36:37], v[52:53], v[62:63] op_sel_hi:[1,0]
	v_pk_mul_f32 v[34:35], v[2:3], v[60:61] op_sel_hi:[1,0]
	v_pk_mul_f32 v[38:39], v[54:55], v[62:63] op_sel_hi:[1,0]
	v_pk_mul_f32 v[32:33], v[32:33], v[212:213]
	v_pk_mul_f32 v[4:5], v[36:37], v[212:213]
	v_pk_mul_f32 v[34:35], v[34:35], v[214:215]
	v_pk_mul_f32 v[6:7], v[38:39], v[214:215]
	v_cvt_pk_bf16_f32 v32, v32, v33
	v_cvt_pk_bf16_f32 v33, v34, v35
	global_store_dwordx2 v[16:17], v[32:33], off offset:1536
	v_cvt_pk_bf16_f32 v4, v4, v5
	v_cvt_pk_bf16_f32 v5, v6, v7
	global_store_dwordx2 v[20:21], v[4:5], off offset:1536
	v_cvt_pk_bf16_f32 v0, v0, v1
	v_cvt_pk_bf16_f32 v1, v2, v3
	global_store_dwordx2 v[18:19], v[0:1], off offset:1536
	v_cvt_pk_bf16_f32 v0, v52, v53
	v_cvt_pk_bf16_f32 v1, v54, v55
	global_store_dwordx2 v[22:23], v[0:1], off offset:1536
	s_cbranch_scc1 .LBB0_218
